# previous best plus: q/k RMS-norm partial sums in the first GEMM epilogue reduced across lane rows with v_permlane16/32_swap instead of two LDS bpermute round trips per row block
# baseline (speedup 1.0000x reference)
;     __device__ __forceinline__ void operator()(f32x4 (&acc)[2][2][4][2], const Unit& u, int wr, int wc, int fr, int fq, LAS unsigned char* lds) const {
;     ...
;                         const f32x4 a = acc[ai][bj][m][0], b = acc[ai][bj][m][1];
;                         float s = (a[0] * a[0] + a[1] * a[1]) + (a[2] * a[2] + a[3] * a[3]) + (b[0] * b[0] + b[1] * b[1]) + (b[2] * b[2] + b[3] * b[3]);
;                         s += __shfl_xor(s, 16); s += __shfl_xor(s, 32);
;                         if (fq == 0) X[((wr * 2 + bj) * 128 + ai * 64 + m * 16 + fr) * 4 + wc] = s;
;                     }
.LBB0_267:
	s_and_b64 vcc, exec, s[66:67]
	s_cbranch_vccz .LBB0_396
	v_mul_f32_e32 v150, v125, v125
	v_mul_f32_e32 v151, v127, v127
	v_fmac_f32_e32 v150, v124, v124
	v_fmac_f32_e32 v151, v126, v126
	v_and_b32_e32 v149, 64, v168
	v_add_f32_e32 v150, v150, v151
	v_mul_f32_e32 v151, v121, v121
	v_xor_b32_e32 v136, 16, v168
	v_add_u32_e32 v149, 64, v149
	v_fmac_f32_e32 v151, v120, v120
	v_cmp_lt_i32_e32 vcc, v136, v149
	v_add_f32_e32 v150, v150, v151
	v_mul_f32_e32 v151, v123, v123
	v_cndmask_b32_e32 v136, v168, v136, vcc
	v_fmac_f32_e32 v151, v122, v122
	v_lshlrev_b32_e32 v136, 2, v136
	v_add_f32_e32 v150, v151, v150
	v_mov_b32_e32 v151, v150
	s_nop 1
	v_permlane16_swap_b32_e32 v150, v151
	v_xor_b32_e32 v152, 32, v168
	v_cmp_lt_i32_e32 vcc, v152, v149
	s_waitcnt lgkmcnt(0)
	v_add_f32_e32 v150, v150, v151
	v_cndmask_b32_e32 v149, v168, v152, vcc
	v_lshlrev_b32_e32 v149, 2, v149
	v_mov_b32_e32 v151, v150
	s_nop 1
	v_permlane32_swap_b32_e32 v150, v151
	s_and_saveexec_b64 s[66:67], s[0:1]
	s_cbranch_execz .LBB0_270
	s_waitcnt lgkmcnt(0)
	v_add_f32_e32 v150, v150, v151
	ds_write_b32 v169, v150
.LBB0_270:
	s_or_b64 exec, exec, s[66:67]
	v_mul_f32_e32 v150, v117, v117
	s_waitcnt lgkmcnt(0)
	v_mul_f32_e32 v151, v119, v119
	v_fmac_f32_e32 v150, v116, v116
	v_fmac_f32_e32 v151, v118, v118
	v_add_f32_e32 v150, v150, v151
	v_mul_f32_e32 v151, v113, v113
	v_fmac_f32_e32 v151, v112, v112
	v_add_f32_e32 v150, v150, v151
	v_mul_f32_e32 v151, v115, v115
	v_fmac_f32_e32 v151, v114, v114
	v_add_f32_e32 v150, v151, v150
	v_mov_b32_e32 v151, v150
	s_nop 1
	v_permlane16_swap_b32_e32 v150, v151
	s_waitcnt lgkmcnt(0)
	v_add_f32_e32 v150, v150, v151
	v_mov_b32_e32 v151, v150
	s_nop 1
	v_permlane32_swap_b32_e32 v150, v151
	s_and_saveexec_b64 s[66:67], s[0:1]
	s_cbranch_execz .LBB0_272
	s_waitcnt lgkmcnt(0)
	v_add_f32_e32 v150, v150, v151
	ds_write_b32 v169, v150 offset:2048
.LBB0_272:
	s_or_b64 exec, exec, s[66:67]
	v_mul_f32_e32 v150, v109, v109
	s_waitcnt lgkmcnt(0)
	v_mul_f32_e32 v151, v111, v111
	v_fmac_f32_e32 v150, v108, v108
	v_fmac_f32_e32 v151, v110, v110
	v_add_f32_e32 v150, v150, v151
	v_mul_f32_e32 v151, v105, v105
	v_fmac_f32_e32 v151, v104, v104
	v_add_f32_e32 v150, v150, v151
	v_mul_f32_e32 v151, v107, v107
	v_fmac_f32_e32 v151, v106, v106
	v_add_f32_e32 v150, v151, v150
	v_mov_b32_e32 v151, v150
	s_nop 1
	v_permlane16_swap_b32_e32 v150, v151
	s_waitcnt lgkmcnt(0)
	v_add_f32_e32 v150, v150, v151
	v_mov_b32_e32 v151, v150
	s_nop 1
	v_permlane32_swap_b32_e32 v150, v151
	s_and_saveexec_b64 s[66:67], s[0:1]
	s_cbranch_execz .LBB0_274
	s_waitcnt lgkmcnt(0)
	v_add_f32_e32 v150, v150, v151
	ds_write_b32 v169, v150 offset:256
.LBB0_274:
	s_or_b64 exec, exec, s[66:67]
	v_mul_f32_e32 v150, v101, v101
	s_waitcnt lgkmcnt(0)
	v_mul_f32_e32 v151, v103, v103
	v_fmac_f32_e32 v150, v100, v100
	v_fmac_f32_e32 v151, v102, v102
	v_add_f32_e32 v150, v150, v151
	v_mul_f32_e32 v151, v97, v97
	v_fmac_f32_e32 v151, v96, v96
	v_add_f32_e32 v150, v150, v151
	v_mul_f32_e32 v151, v99, v99
	v_fmac_f32_e32 v151, v98, v98
	v_add_f32_e32 v150, v151, v150
	v_mov_b32_e32 v151, v150
	s_nop 1
	v_permlane16_swap_b32_e32 v150, v151
	s_waitcnt lgkmcnt(0)
	v_add_f32_e32 v150, v150, v151
	v_mov_b32_e32 v151, v150
	s_nop 1
	v_permlane32_swap_b32_e32 v150, v151
	s_and_saveexec_b64 s[66:67], s[0:1]
	s_cbranch_execz .LBB0_276
	s_waitcnt lgkmcnt(0)
	v_add_f32_e32 v150, v150, v151
	ds_write_b32 v169, v150 offset:2304
.LBB0_276:
	s_or_b64 exec, exec, s[66:67]
	v_mul_f32_e32 v150, v93, v93
	s_waitcnt lgkmcnt(0)
	v_mul_f32_e32 v151, v95, v95
	v_fmac_f32_e32 v150, v92, v92
	v_fmac_f32_e32 v151, v94, v94
	v_add_f32_e32 v150, v150, v151
	v_mul_f32_e32 v151, v89, v89
	v_fmac_f32_e32 v151, v88, v88
	v_add_f32_e32 v150, v150, v151
	v_mul_f32_e32 v151, v91, v91
	v_fmac_f32_e32 v151, v90, v90
	v_add_f32_e32 v150, v151, v150
	v_mov_b32_e32 v151, v150
	s_nop 1
	v_permlane16_swap_b32_e32 v150, v151
	s_waitcnt lgkmcnt(0)
	v_add_f32_e32 v150, v150, v151
	v_mov_b32_e32 v151, v150
	s_nop 1
	v_permlane32_swap_b32_e32 v150, v151
	s_and_saveexec_b64 s[66:67], s[0:1]
	s_cbranch_execz .LBB0_278
	s_waitcnt lgkmcnt(0)
	v_add_f32_e32 v150, v150, v151
	ds_write_b32 v169, v150 offset:512
.LBB0_278:
	s_or_b64 exec, exec, s[66:67]
	v_mul_f32_e32 v150, v85, v85
	s_waitcnt lgkmcnt(0)
	v_mul_f32_e32 v151, v87, v87
	v_fmac_f32_e32 v150, v84, v84
	v_fmac_f32_e32 v151, v86, v86
	v_add_f32_e32 v150, v150, v151
	v_mul_f32_e32 v151, v81, v81
	v_fmac_f32_e32 v151, v80, v80
	v_add_f32_e32 v150, v150, v151
	v_mul_f32_e32 v151, v83, v83
	v_fmac_f32_e32 v151, v82, v82
	v_add_f32_e32 v150, v151, v150
	v_mov_b32_e32 v151, v150
	s_nop 1
	v_permlane16_swap_b32_e32 v150, v151
	s_waitcnt lgkmcnt(0)
	v_add_f32_e32 v150, v150, v151
	v_mov_b32_e32 v151, v150
	s_nop 1
	v_permlane32_swap_b32_e32 v150, v151
	s_and_saveexec_b64 s[66:67], s[0:1]
	s_cbranch_execz .LBB0_280
	s_waitcnt lgkmcnt(0)
	v_add_f32_e32 v150, v150, v151
	ds_write_b32 v169, v150 offset:2560
.LBB0_280:
	s_or_b64 exec, exec, s[66:67]
	v_mul_f32_e32 v150, v77, v77
	s_waitcnt lgkmcnt(0)
	v_mul_f32_e32 v151, v79, v79
	v_fmac_f32_e32 v150, v76, v76
	v_fmac_f32_e32 v151, v78, v78
	v_add_f32_e32 v150, v150, v151
	v_mul_f32_e32 v151, v73, v73
	v_fmac_f32_e32 v151, v72, v72
	v_add_f32_e32 v150, v150, v151
	v_mul_f32_e32 v151, v75, v75
	v_fmac_f32_e32 v151, v74, v74
	v_add_f32_e32 v150, v151, v150
	v_mov_b32_e32 v151, v150
	s_nop 1
	v_permlane16_swap_b32_e32 v150, v151
	s_waitcnt lgkmcnt(0)
	v_add_f32_e32 v150, v150, v151
	v_mov_b32_e32 v151, v150
	s_nop 1
	v_permlane32_swap_b32_e32 v150, v151
	s_and_saveexec_b64 s[66:67], s[0:1]
	s_cbranch_execz .LBB0_282
	s_waitcnt lgkmcnt(0)
	v_add_f32_e32 v150, v150, v151
	ds_write_b32 v169, v150 offset:768
;     __device__ __forceinline__ void operator()(f32x4 (&acc)[2][2][4][2], const Unit& u, int wr, int wc, int fr, int fq, LAS unsigned char* lds) const {
;     ...
;                         const f32x4 a = acc[ai][bj][m][0], b = acc[ai][bj][m][1];
;                         float s = (a[0] * a[0] + a[1] * a[1]) + (a[2] * a[2] + a[3] * a[3]) + (b[0] * b[0] + b[1] * b[1]) + (b[2] * b[2] + b[3] * b[3]);
;                         s += __shfl_xor(s, 16); s += __shfl_xor(s, 32);
;                         if (fq == 0) X[((wr * 2 + bj) * 128 + ai * 64 + m * 16 + fr) * 4 + wc] = s;
;                     }
.LBB0_282:
	s_or_b64 exec, exec, s[66:67]
	v_mul_f32_e32 v150, v69, v69
	s_waitcnt lgkmcnt(0)
	v_mul_f32_e32 v151, v71, v71
	v_fmac_f32_e32 v150, v68, v68
	v_fmac_f32_e32 v151, v70, v70
	v_add_f32_e32 v150, v150, v151
	v_mul_f32_e32 v151, v65, v65
	v_fmac_f32_e32 v151, v64, v64
	v_add_f32_e32 v150, v150, v151
	v_mul_f32_e32 v151, v67, v67
	v_fmac_f32_e32 v151, v66, v66
	v_add_f32_e32 v150, v151, v150
	v_mov_b32_e32 v151, v150
	s_nop 1
	v_permlane16_swap_b32_e32 v150, v151
	s_waitcnt lgkmcnt(0)
	v_add_f32_e32 v150, v150, v151
	v_mov_b32_e32 v151, v150
	s_nop 1
	v_permlane32_swap_b32_e32 v150, v151
	s_and_saveexec_b64 s[66:67], s[0:1]
	s_cbranch_execz .LBB0_284
	s_waitcnt lgkmcnt(0)
	v_add_f32_e32 v150, v150, v151
	ds_write_b32 v169, v150 offset:2816
.LBB0_284:
	s_or_b64 exec, exec, s[66:67]
	v_mul_f32_e32 v150, v61, v61
	s_waitcnt lgkmcnt(0)
	v_mul_f32_e32 v151, v63, v63
	v_fmac_f32_e32 v150, v60, v60
	v_fmac_f32_e32 v151, v62, v62
	v_add_f32_e32 v150, v150, v151
	v_mul_f32_e32 v151, v57, v57
	v_fmac_f32_e32 v151, v56, v56
	v_add_f32_e32 v150, v150, v151
	v_mul_f32_e32 v151, v59, v59
	v_fmac_f32_e32 v151, v58, v58
	v_add_f32_e32 v150, v151, v150
	v_mov_b32_e32 v151, v150
	s_nop 1
	v_permlane16_swap_b32_e32 v150, v151
	s_waitcnt lgkmcnt(0)
	v_add_f32_e32 v150, v150, v151
	v_mov_b32_e32 v151, v150
	s_nop 1
	v_permlane32_swap_b32_e32 v150, v151
	s_and_saveexec_b64 s[66:67], s[0:1]
	s_cbranch_execz .LBB0_286
	s_waitcnt lgkmcnt(0)
	v_add_f32_e32 v150, v150, v151
	ds_write_b32 v169, v150 offset:1024
.LBB0_286:
	s_or_b64 exec, exec, s[66:67]
	v_mul_f32_e32 v150, v53, v53
	s_waitcnt lgkmcnt(0)
	v_mul_f32_e32 v151, v55, v55
	v_fmac_f32_e32 v150, v52, v52
	v_fmac_f32_e32 v151, v54, v54
	v_add_f32_e32 v150, v150, v151
	v_mul_f32_e32 v151, v49, v49
	v_fmac_f32_e32 v151, v48, v48
	v_add_f32_e32 v150, v150, v151
	v_mul_f32_e32 v151, v51, v51
	v_fmac_f32_e32 v151, v50, v50
	v_add_f32_e32 v150, v151, v150
	v_mov_b32_e32 v151, v150
	s_nop 1
	v_permlane16_swap_b32_e32 v150, v151
	s_waitcnt lgkmcnt(0)
	v_add_f32_e32 v150, v150, v151
	v_mov_b32_e32 v151, v150
	s_nop 1
	v_permlane32_swap_b32_e32 v150, v151
	s_and_saveexec_b64 s[66:67], s[0:1]
	s_cbranch_execz .LBB0_288
	s_waitcnt lgkmcnt(0)
	v_add_f32_e32 v150, v150, v151
	ds_write_b32 v169, v150 offset:3072
.LBB0_288:
	s_or_b64 exec, exec, s[66:67]
	v_mul_f32_e32 v150, v45, v45
	s_waitcnt lgkmcnt(0)
	v_mul_f32_e32 v151, v47, v47
	v_fmac_f32_e32 v150, v44, v44
	v_fmac_f32_e32 v151, v46, v46
	v_add_f32_e32 v150, v150, v151
	v_mul_f32_e32 v151, v41, v41
	v_fmac_f32_e32 v151, v40, v40
	v_add_f32_e32 v150, v150, v151
	v_mul_f32_e32 v151, v43, v43
	v_fmac_f32_e32 v151, v42, v42
	v_add_f32_e32 v150, v151, v150
	v_mov_b32_e32 v151, v150
	s_nop 1
	v_permlane16_swap_b32_e32 v150, v151
	s_waitcnt lgkmcnt(0)
	v_add_f32_e32 v150, v150, v151
	v_mov_b32_e32 v151, v150
	s_nop 1
	v_permlane32_swap_b32_e32 v150, v151
	s_and_saveexec_b64 s[66:67], s[0:1]
	s_cbranch_execz .LBB0_290
	s_waitcnt lgkmcnt(0)
	v_add_f32_e32 v150, v150, v151
	ds_write_b32 v169, v150 offset:1280
.LBB0_290:
	s_or_b64 exec, exec, s[66:67]
	v_mul_f32_e32 v150, v37, v37
	s_waitcnt lgkmcnt(0)
	v_mul_f32_e32 v151, v39, v39
	v_fmac_f32_e32 v150, v36, v36
	v_fmac_f32_e32 v151, v38, v38
	v_add_f32_e32 v150, v150, v151
	v_mul_f32_e32 v151, v33, v33
	v_fmac_f32_e32 v151, v32, v32
	v_add_f32_e32 v150, v150, v151
	v_mul_f32_e32 v151, v35, v35
	v_fmac_f32_e32 v151, v34, v34
	v_add_f32_e32 v150, v151, v150
	v_mov_b32_e32 v151, v150
	s_nop 1
	v_permlane16_swap_b32_e32 v150, v151
	s_waitcnt lgkmcnt(0)
	v_add_f32_e32 v150, v150, v151
	v_mov_b32_e32 v151, v150
	s_nop 1
	v_permlane32_swap_b32_e32 v150, v151
	s_and_saveexec_b64 s[66:67], s[0:1]
	s_cbranch_execz .LBB0_292
	s_waitcnt lgkmcnt(0)
	v_add_f32_e32 v150, v150, v151
	ds_write_b32 v169, v150 offset:3328
.LBB0_292:
	s_or_b64 exec, exec, s[66:67]
	v_mul_f32_e32 v150, v29, v29
	s_waitcnt lgkmcnt(0)
	v_mul_f32_e32 v151, v31, v31
	v_fmac_f32_e32 v150, v28, v28
	v_fmac_f32_e32 v151, v30, v30
	v_add_f32_e32 v150, v150, v151
	v_mul_f32_e32 v151, v25, v25
	v_fmac_f32_e32 v151, v24, v24
	v_add_f32_e32 v150, v150, v151
	v_mul_f32_e32 v151, v27, v27
	v_fmac_f32_e32 v151, v26, v26
	v_add_f32_e32 v150, v151, v150
	v_mov_b32_e32 v151, v150
	s_nop 1
	v_permlane16_swap_b32_e32 v150, v151
	s_waitcnt lgkmcnt(0)
	v_add_f32_e32 v150, v150, v151
	v_mov_b32_e32 v151, v150
	s_nop 1
	v_permlane32_swap_b32_e32 v150, v151
	s_and_saveexec_b64 s[66:67], s[0:1]
	s_cbranch_execz .LBB0_294
	s_waitcnt lgkmcnt(0)
	v_add_f32_e32 v150, v150, v151
	ds_write_b32 v169, v150 offset:1536
.LBB0_294:
	s_or_b64 exec, exec, s[66:67]
	v_mul_f32_e32 v150, v21, v21
	s_waitcnt lgkmcnt(0)
	v_mul_f32_e32 v151, v23, v23
	v_fmac_f32_e32 v150, v20, v20
	v_fmac_f32_e32 v151, v22, v22
	v_add_f32_e32 v150, v150, v151
	v_mul_f32_e32 v151, v17, v17
	v_fmac_f32_e32 v151, v16, v16
	v_add_f32_e32 v150, v150, v151
	v_mul_f32_e32 v151, v19, v19
	v_fmac_f32_e32 v151, v18, v18
	v_add_f32_e32 v150, v151, v150
	v_mov_b32_e32 v151, v150
	s_nop 1
	v_permlane16_swap_b32_e32 v150, v151
	s_waitcnt lgkmcnt(0)
	v_add_f32_e32 v150, v150, v151
	v_mov_b32_e32 v151, v150
	s_nop 1
	v_permlane32_swap_b32_e32 v150, v151
	s_and_saveexec_b64 s[66:67], s[0:1]
	s_cbranch_execz .LBB0_296
	s_waitcnt lgkmcnt(0)
	v_add_f32_e32 v150, v150, v151
	ds_write_b32 v169, v150 offset:3584
.LBB0_296:
	s_or_b64 exec, exec, s[66:67]
	v_mul_f32_e32 v150, v13, v13
	s_waitcnt lgkmcnt(0)
	v_mul_f32_e32 v151, v15, v15
	v_fmac_f32_e32 v150, v12, v12
	v_fmac_f32_e32 v151, v14, v14
	v_add_f32_e32 v150, v150, v151
	v_mul_f32_e32 v151, v9, v9
	v_fmac_f32_e32 v151, v8, v8
	v_add_f32_e32 v150, v150, v151
	v_mul_f32_e32 v151, v11, v11
	v_fmac_f32_e32 v151, v10, v10
	v_add_f32_e32 v150, v151, v150
	v_mov_b32_e32 v151, v150
	s_nop 1
	v_permlane16_swap_b32_e32 v150, v151
	s_waitcnt lgkmcnt(0)
	v_add_f32_e32 v150, v150, v151
	v_mov_b32_e32 v151, v150
	s_nop 1
	v_permlane32_swap_b32_e32 v150, v151
	s_and_saveexec_b64 s[66:67], s[0:1]
	s_cbranch_execz .LBB0_298
	s_waitcnt lgkmcnt(0)
	v_add_f32_e32 v150, v150, v151
	ds_write_b32 v169, v150 offset:1792
.LBB0_298:
	s_or_b64 exec, exec, s[66:67]
	v_mul_f32_e32 v150, v5, v5
	s_waitcnt lgkmcnt(0)
	v_mul_f32_e32 v151, v7, v7
	v_fmac_f32_e32 v150, v4, v4
	v_fmac_f32_e32 v151, v6, v6
	v_add_f32_e32 v150, v150, v151
	v_mul_f32_e32 v151, v1, v1
	v_fmac_f32_e32 v151, v0, v0
	v_add_f32_e32 v150, v150, v151
	v_mul_f32_e32 v151, v3, v3
	v_fmac_f32_e32 v151, v2, v2
	v_add_f32_e32 v150, v151, v150
	v_mov_b32_e32 v136, v150
	s_nop 1
	v_permlane16_swap_b32_e32 v150, v136
	s_waitcnt lgkmcnt(0)
	v_add_f32_e32 v136, v150, v136
	v_mov_b32_e32 v149, v136
	s_nop 1
	v_permlane32_swap_b32_e32 v136, v149
	s_and_saveexec_b64 s[66:67], s[0:1]
	s_cbranch_execz .LBB0_300
	s_waitcnt lgkmcnt(0)
	v_add_f32_e32 v136, v136, v149
	ds_write_b32 v169, v136 offset:3840
